# barS set-up sweep: all 16 counter loads issued together (one vmcnt(0)) instead of 6 serialized tail loads
# baseline (speedup 1.0000x reference)
.LBB0_841:
	v_readlane_b32 s2, v250, 15
	v_readlane_b32 s3, v250, 16
	global_load_dword v8, v16, s[12:13] sc1
	global_load_dword v0, v16, s[18:19] sc1
	global_load_dword v1, v16, s[20:21] sc1
	global_load_dword v2, v16, s[22:23] sc1
	global_load_dword v3, v16, s[24:25] sc1
	global_load_dword v4, v16, s[28:29] sc1
	global_load_dword v5, v16, s[30:31] sc1
	global_load_dword v6, v16, s[36:37] sc1
	global_load_dword v7, v16, s[38:39] sc1
	global_load_dword v9, v16, s[2:3] sc1
	global_load_dword v10, v16, s[2:3] offset:256 sc1
	global_load_dword v11, v16, s[2:3] offset:512 sc1
	global_load_dword v12, v16, s[2:3] offset:768 sc1
	global_load_dword v13, v16, s[2:3] offset:1024 sc1
	global_load_dword v14, v16, s[2:3] offset:1280 sc1
	global_load_dword v15, v16, s[2:3] offset:1536 sc1
	s_mov_b64 s[4:5], -1
	s_waitcnt vmcnt(0)
	v_add_u32_e32 v17, v0, v8
	v_add_u32_e32 v17, v17, v1
	v_add_u32_e32 v17, v17, v2
	v_add_u32_e32 v17, v17, v3
	v_add_u32_e32 v17, v17, v4
	v_add_u32_e32 v17, v17, v5
	v_add_u32_e32 v17, v17, v6
	v_add_u32_e32 v17, v17, v7
	v_add_u32_e32 v17, v17, v9
	v_add_u32_e32 v17, v17, v10
	v_add_u32_e32 v17, v17, v11
	v_add_u32_e32 v17, v17, v12
	v_add_u32_e32 v17, v17, v13
	v_add_u32_e32 v17, v17, v14
	s_mov_b64 s[2:3], -1
	v_add_u32_e32 v17, v17, v15
	v_cmp_eq_u32_e32 vcc, s8, v17
	s_cbranch_vccnz .LBB0_840
	s_and_b32 s2, s9, 0xff
	s_cmp_eq_u32 s2, 0
	s_mov_b64 s[2:3], -1
	s_mov_b64 s[6:7], -1
	s_sleep 1
	s_cbranch_scc1 .LBB0_845
	s_and_b64 vcc, exec, s[6:7]
	s_cbranch_vccz .LBB0_840
